# P4 side job skipped on kv-iterations with (j&3)==3 to spread its HBM traffic into the context units
# baseline (speedup 1.0000x reference)
.LBB0_411:
	v_lshl_add_u64 v[72:73], v[72:73], 1, s[2:3]
	v_lshl_add_u64 v[70:71], v[70:71], 1, s[2:3]
	v_add_u32_e32 v2, 0x80, v2
	global_load_dwordx4 v[132:135], v[72:73], off
	global_load_dwordx4 v[136:139], v[70:71], off
	v_lshl_add_u64 v[68:69], v[68:69], 1, s[2:3]
	v_lshl_add_u64 v[70:71], v[2:3], 1, s[2:3]
	s_lshl_b64 s[2:3], s[4:5], 12
	s_add_u32 s2, s60, s2
	s_addc_u32 s3, s61, s3
	global_load_dwordx4 v[144:147], v[68:69], off
	global_load_dwordx4 v[140:143], v[70:71], off
	v_lshl_add_u64 v[68:69], v[162:163], 1, s[2:3]
	v_lshl_add_u64 v[70:71], v[180:181], 1, s[2:3]
	global_load_dwordx4 v[152:155], v[68:69], off
	global_load_dwordx4 v[148:151], v[70:71], off
	s_and_b32 s98, s8, 3
	s_cmp_eq_u32 s98, 3
	s_cselect_b32 s98, 0x7fffffff, s19
	s_cmp_lt_i32 s98, 0x14000
	s_cselect_b64 s[66:67], -1, 0
	s_cmp_gt_i32 s98, 0x13fff
	s_cbranch_scc1 .LBB0_413
	s_add_i32 s2, s19, 0xffff0000
	s_cmp_gt_i32 s19, 0xffff
	s_cselect_b32 s4, s2, s19
	s_cselect_b32 s5, s41, s47
	s_cselect_b32 s9, s40, s46
	s_ashr_i32 s2, s4, 2
	s_and_b32 s2, s2, -8
	s_ashr_i32 s3, s2, 31
	s_lshl_b64 s[2:3], s[2:3], 14
	s_add_u32 s2, s9, s2
	s_addc_u32 s3, s5, s3
	s_lshl_b32 s4, s4, 9
	s_and_b32 s4, s4, 0x3e00
	s_add_u32 s2, s2, s4
	s_addc_u32 s3, s3, 0
	v_lshlrev_b32_e32 v2, 2, v158
	v_lshl_add_u64 v[68:69], s[2:3], 0, v[2:3]
	v_add_co_u32_e32 v70, vcc, s26, v68
	global_load_dwordx2 v[184:185], v2, s[2:3] nt
	s_nop 0
	v_addc_co_u32_e32 v71, vcc, 0, v69, vcc
	global_load_dwordx2 v[186:187], v[70:71], off nt
	v_add_co_u32_e32 v70, vcc, 0x8000, v68
	s_nop 1
	v_addc_co_u32_e32 v71, vcc, 0, v69, vcc
	global_load_dwordx2 v[188:189], v[70:71], off nt
	v_add_co_u32_e32 v70, vcc, 0xc000, v68
	s_nop 1
	v_addc_co_u32_e32 v71, vcc, 0, v69, vcc
	global_load_dwordx2 v[190:191], v[70:71], off nt
	v_add_co_u32_e32 v70, vcc, 0x10000, v68
	s_nop 1
	v_addc_co_u32_e32 v71, vcc, 0, v69, vcc
	global_load_dwordx2 v[192:193], v[70:71], off nt
	v_add_co_u32_e32 v70, vcc, 0x14000, v68
	s_nop 1
	v_addc_co_u32_e32 v71, vcc, 0, v69, vcc
	global_load_dwordx2 v[194:195], v[70:71], off nt
	v_add_co_u32_e32 v70, vcc, 0x18000, v68
	s_nop 1
	v_addc_co_u32_e32 v71, vcc, 0, v69, vcc
	v_add_co_u32_e32 v68, vcc, 0x1c000, v68
	global_load_dwordx2 v[196:197], v[70:71], off nt
	s_nop 0
	v_addc_co_u32_e32 v69, vcc, 0, v69, vcc
	global_load_dwordx2 v[198:199], v[68:69], off nt

	.amdhsa_kernel _Z6mk_fwd4Args
		.amdhsa_group_segment_fixed_size 0
		.amdhsa_private_segment_fixed_size 0
		.amdhsa_kernarg_size 456
		.amdhsa_user_sgpr_count 2
		.amdhsa_user_sgpr_dispatch_ptr 0
		.amdhsa_user_sgpr_queue_ptr 0
		.amdhsa_user_sgpr_kernarg_segment_ptr 1
		.amdhsa_user_sgpr_dispatch_id 0
		.amdhsa_user_sgpr_kernarg_preload_length 0
		.amdhsa_user_sgpr_kernarg_preload_offset 0
		.amdhsa_user_sgpr_private_segment_size 0
		.amdhsa_uses_dynamic_stack 0
		.amdhsa_enable_private_segment 0
		.amdhsa_system_sgpr_workgroup_id_x 1
		.amdhsa_system_sgpr_workgroup_id_y 0
		.amdhsa_system_sgpr_workgroup_id_z 0
		.amdhsa_system_sgpr_workgroup_info 0
		.amdhsa_system_vgpr_workitem_id 0
		.amdhsa_next_free_vgpr 250
		.amdhsa_next_free_sgpr 100
		.amdhsa_accum_offset 252
		.amdhsa_reserve_vcc 1
		.amdhsa_float_round_mode_32 0
		.amdhsa_float_round_mode_16_64 0
		.amdhsa_float_denorm_mode_32 3
		.amdhsa_float_denorm_mode_16_64 3
		.amdhsa_dx10_clamp 1
		.amdhsa_ieee_mode 1
		.amdhsa_fp16_overflow 0
		.amdhsa_tg_split 0
		.amdhsa_exception_fp_ieee_invalid_op 0
		.amdhsa_exception_fp_denorm_src 0
		.amdhsa_exception_fp_ieee_div_zero 0
		.amdhsa_exception_fp_ieee_overflow 0
		.amdhsa_exception_fp_ieee_underflow 0
		.amdhsa_exception_fp_ieee_inexact 0
		.amdhsa_exception_int_div_zero 0
	.end_amdhsa_kernel

amdhsa.kernels:
  - .agpr_count:     0
    .args:
      - .offset:         0
        .size:           200
        .value_kind:     by_value
      - .offset:         200
        .size:           4
        .value_kind:     hidden_block_count_x
      - .offset:         204
        .size:           4
        .value_kind:     hidden_block_count_y
      - .offset:         208
        .size:           4
        .value_kind:     hidden_block_count_z
      - .offset:         212
        .size:           2
        .value_kind:     hidden_group_size_x
      - .offset:         214
        .size:           2
        .value_kind:     hidden_group_size_y
      - .offset:         216
        .size:           2
        .value_kind:     hidden_group_size_z
      - .offset:         218
        .size:           2
        .value_kind:     hidden_remainder_x
      - .offset:         220
        .size:           2
        .value_kind:     hidden_remainder_y
      - .offset:         222
        .size:           2
        .value_kind:     hidden_remainder_z
      - .offset:         240
        .size:           8
        .value_kind:     hidden_global_offset_x
      - .offset:         248
        .size:           8
        .value_kind:     hidden_global_offset_y
      - .offset:         256
        .size:           8
        .value_kind:     hidden_global_offset_z
      - .offset:         264
        .size:           2
        .value_kind:     hidden_grid_dims
      - .offset:         320
        .size:           4
        .value_kind:     hidden_dynamic_lds_size
    .group_segment_fixed_size: 0
    .kernarg_segment_align: 8
    .kernarg_segment_size: 456
    .language:       OpenCL C
    .language_version:
      - 2
      - 0
    .max_flat_workgroup_size: 512
    .name:           _Z6mk_fwd4Args
    .private_segment_fixed_size: 0
    .sgpr_count:     106
    .sgpr_spill_count: 79
    .symbol:         _Z6mk_fwd4Args.kd
    .uniform_work_group_size: 1
    .uses_dynamic_stack: false
    .vgpr_count:     250
    .vgpr_spill_count: 0
    .wavefront_size: 64
